# mode-3 GEMM epilogue head: gate/gn/scn vector loads batched (12 loads in flight, one wait) instead of 4 dependent load-wait-compute groups
# speedup vs baseline: 1.0041x; 1.0041x over previous
.LBB0_268:
	s_lshl_b64 s[44:45], s[44:45], 2
	v_readlane_b32 s48, v248, 4
	v_lshl_or_b32 v184, s56, 8, v228
	v_readlane_b32 s49, v248, 5
	s_add_u32 s48, s48, s44
	v_ashrrev_i32_e32 v185, 31, v184
	s_addc_u32 s49, s49, s45
	v_lshlrev_b64 v[128:129], 2, v[184:185]
	v_lshl_add_u64 v[132:133], s[48:49], 0, v[128:129]
	v_readlane_b32 s48, v248, 2
	v_readlane_b32 s49, v248, 3
	v_mov_b32_e32 v186, 0
	v_mov_b32_e32 v188, 0
	v_lshl_add_u64 v[144:145], s[48:49], 0, v[128:129]
	v_readlane_b32 s48, v248, 0
	v_readlane_b32 s49, v248, 1
	s_add_u32 s44, s48, s44
	s_addc_u32 s45, s49, s45
	v_readlane_b32 s48, v248, 24
	v_readlane_b32 s49, v248, 25
	v_lshl_add_u64 v[146:147], s[44:45], 0, v[128:129]
	s_andn2_b64 vcc, exec, s[48:49]
	v_cndmask_b32_e64 v128, 0, 1, s[48:49]
	v_cmp_ne_u32_e64 s[44:45], 1, v128
	v_mov_b32_e32 v187, 0
	v_mov_b32_e32 v189, 0
	v_mov_b32_e32 v190, 0
	v_mov_b32_e32 v191, 0
	v_mov_b32_e32 v192, 0
	v_mov_b32_e32 v193, 0
	v_mov_b32_e32 v176, 0
	v_mov_b32_e32 v177, 0
	v_mov_b32_e32 v178, 0
	v_mov_b32_e32 v179, 0
	v_mov_b32_e32 v180, 0
	v_mov_b32_e32 v181, 0
	v_mov_b32_e32 v182, 0
	v_mov_b32_e32 v183, 0
	global_load_dwordx4 v[136:139], v[132:133], off
	global_load_dwordx4 v[140:143], v[132:133], off offset:16
	global_load_dwordx4 v[128:131], v[132:133], off offset:512
	s_nop 0
	global_load_dwordx4 v[132:135], v[132:133], off offset:528
	s_cbranch_vccnz .Lepi3_nogm
	global_load_dwordx4 v[234:237], v[146:147], off
	global_load_dwordx4 v[238:241], v[146:147], off offset:16
	global_load_dwordx4 v[242:245], v[146:147], off offset:512
	global_load_dwordx4 v[198:201], v[146:147], off offset:528
	global_load_dwordx4 v[148:151], v[144:145], off
	global_load_dwordx4 v[194:197], v[144:145], off offset:16
	global_load_dwordx4 v[202:205], v[144:145], off offset:512
	global_load_dwordx4 v[206:209], v[144:145], off offset:528
	s_waitcnt vmcnt(0)
	v_pk_add_f32 v[236:237], v[236:237], 1.0 op_sel_hi:[1,0]
	v_pk_add_f32 v[234:235], v[234:235], 1.0 op_sel_hi:[1,0]
	v_pk_add_f32 v[240:241], v[240:241], 1.0 op_sel_hi:[1,0]
	v_pk_add_f32 v[238:239], v[238:239], 1.0 op_sel_hi:[1,0]
	v_pk_add_f32 v[244:245], v[244:245], 1.0 op_sel_hi:[1,0]
	v_pk_add_f32 v[242:243], v[242:243], 1.0 op_sel_hi:[1,0]
	v_pk_add_f32 v[200:201], v[200:201], 1.0 op_sel_hi:[1,0]
	v_pk_add_f32 v[198:199], v[198:199], 1.0 op_sel_hi:[1,0]
	v_pk_mul_f32 v[190:191], v[150:151], v[236:237]
	v_pk_mul_f32 v[188:189], v[148:149], v[234:235]
	v_pk_mul_f32 v[192:193], v[196:197], v[240:241]
	v_pk_mul_f32 v[186:187], v[194:195], v[238:239]
	v_pk_mul_f32 v[180:181], v[204:205], v[244:245]
	v_pk_mul_f32 v[178:179], v[202:203], v[242:243]
	v_pk_mul_f32 v[182:183], v[208:209], v[200:201]
	v_pk_mul_f32 v[176:177], v[206:207], v[198:199]
.Lepi3_nogm:
.LBB0_276:
	s_add_i32 s68, s23, 0xffff8000
	s_and_b64 s[48:49], s[46:47], exec
	s_cselect_b32 s23, s23, s68
	v_readlane_b32 s48, v248, 10
	v_readlane_b32 s68, v248, 8
	v_add_u32_e32 v194, s23, v225
	v_readlane_b32 s49, v248, 11
	v_readlane_b32 s69, v248, 9
	s_cselect_b32 s71, s49, s69
	s_cselect_b32 s70, s48, s68
	v_readlane_b32 s48, v248, 6
	v_readlane_b32 s68, v248, 12
	v_ashrrev_i32_e32 v195, 31, v194
	v_readlane_b32 s49, v248, 7
	v_readlane_b32 s69, v248, 13
	v_lshlrev_b64 v[144:145], 10, v[194:195]
	s_cselect_b32 s69, s69, s49
	s_cselect_b32 s68, s68, s48
	s_cmp_lg_u64 s[70:71], 0
	v_lshl_add_u64 v[196:197], v[144:145], 0, v[184:185]
	s_cselect_b64 s[48:49], -1, 0
	s_cmp_eq_u64 s[70:71], 0
	v_lshl_add_u64 v[208:209], v[196:197], 2, s[70:71]
	s_cbranch_scc1 .LBB0_473
	v_lshlrev_b32_e32 v246, 2, v196
	global_load_dwordx4 v[236:239], v246, s[70:71]
	global_load_dwordx4 v[240:243], v246, s[70:71] offset:16
	s_waitcnt vmcnt(0)
	v_mov_b32_e32 v148, v236
	v_mov_b32_e32 v149, v237
	v_mov_b32_e32 v150, v238
	v_mov_b32_e32 v151, v239
	v_mov_b32_e32 v144, v240
	v_mov_b32_e32 v145, v241
	v_mov_b32_e32 v146, v242
	v_mov_b32_e32 v147, v243
	global_load_dwordx4 v[236:239], v246, s[70:71] offset:512
	global_load_dwordx4 v[240:243], v246, s[70:71] offset:528
	s_mov_b32 s23, s81
	v_lshl_add_u64 v[210:211], v[196:197], 1, s[68:69]
	s_cbranch_execnz .LBB0_279
